# v021 + rmsnorm-mode mixer-in epilogue: the four gain-vector loads issued together at the top (one wait instead of a serialized second batch)
# baseline (speedup 1.0000x reference)
;     __device__ __forceinline__ void operator()(const f32x4 (&acc)[2][2][4][2], const Unit& u, int wr, int wc, int fr, int fq, float rp0, float rp1, const f32x4& raw0, const f32x4& raw1, float& rn0, float& rn1) const {
;     ...
;         if (mode == 2) {
;             f32x4 g[2][2];
; #pragma unroll
;             for (int bj = 0; bj < 2; ++bj)
; #pragma unroll
;                 for (int n = 0; n < 2; ++n) g[bj][n] = *(const f32x4*)(gain + bj * 32 + 8 * fq + 4 * n) * scale;
; #pragma unroll
;             for (int ai = 0; ai < 2; ++ai) {
;                 float rs[4];
; #pragma unroll
;                 for (int k = 0; k < 4; ++k) rs[k] = __shfl(ai ? rp1 : rp0, fr + 16 * k);
; #pragma unroll
;                 for (int m = 0; m < 4; ++m) {
;                     const int roff = ai * HALF + m * 16; const float r = rs[m];
;                     const f32x4 v00 = acc[ai][0][m][0] * r, v01 = acc[ai][0][m][1] * r, v10 = acc[ai][1][m][0] * r, v11 = acc[ai][1][m][1] * r;
;                     const f32x4 sq4 = (v00 * v00 + v01 * v01) + (v10 * v10 + v11 * v11);
;                     float ss = (sq4[0] + sq4[1]) + (sq4[2] + sq4[3]);
;                     ss += __shfl_xor(ss, 16); ss += __shfl_xor(ss, 32);
;                     const float rr = rsqrtf(ss * (1.f / 64.f) + EPS);
.LBB0_165:
	s_and_b64 vcc, exec, s[42:43]
	s_cbranch_vccz .LBB0_167
	global_load_dwordx4 v[162:165], v194, s[92:93] offset:16
	global_load_dwordx4 v[158:161], v194, s[92:93]
	global_load_dwordx4 v[220:223], v194, s[92:93] offset:144
	global_load_dwordx4 v[224:227], v194, s[92:93] offset:128
	v_or_b32_e32 v170, v254, v173
	v_lshlrev_b32_e32 v196, 2, v170
	ds_bpermute_b32 v198, v196, v155
	ds_bpermute_b32 v200, v196, v155 offset:64
	v_cmp_lt_i32_e32 vcc, v213, v208
	s_mov_b32 s6, 0x358637bd
	ds_bpermute_b32 v172, v196, v155 offset:128
	s_waitcnt lgkmcnt(0)
	v_pk_mul_f32 v[116:117], v[116:117], v[198:199] op_sel_hi:[1,0]
	v_pk_mul_f32 v[122:123], v[122:123], v[198:199] op_sel_hi:[1,0]
	v_pk_mul_f32 v[104:105], v[104:105], v[200:201] op_sel_hi:[1,0]
	v_pk_mul_f32 v[110:111], v[110:111], v[200:201] op_sel_hi:[1,0]
	v_pk_mul_f32 v[100:101], v[100:101], v[200:201] op_sel_hi:[1,0]
	v_cndmask_b32_e32 v171, v197, v213, vcc
	v_lshlrev_b32_e32 v195, 2, v171
	v_cmp_lt_i32_e32 vcc, v214, v208
	s_lshl_b32 s76, s10, 5
	ds_bpermute_b32 v170, v196, v155 offset:192
	v_cndmask_b32_e32 v171, v197, v214, vcc
	v_lshlrev_b32_e32 v171, 2, v171
	v_pk_mul_f32 v[80:81], v[80:81], v[172:173] op_sel_hi:[1,0]
	v_pk_mul_f32 v[78:79], v[78:79], v[172:173] op_sel_hi:[1,0]
	v_pk_mul_f32 v[96:97], v[96:97], v[172:173] op_sel_hi:[1,0]
	v_pk_mul_f32 v[94:95], v[94:95], v[172:173] op_sel_hi:[1,0]
	v_pk_mul_f32 v[76:77], v[76:77], v[172:173] op_sel_hi:[1,0]
	v_pk_mul_f32 v[74:75], v[74:75], v[172:173] op_sel_hi:[1,0]
	v_pk_mul_f32 v[92:93], v[92:93], v[172:173] op_sel_hi:[1,0]
	v_pk_mul_f32 v[90:91], v[90:91], v[172:173] op_sel_hi:[1,0]
	s_waitcnt lgkmcnt(0)
	v_pk_mul_f32 v[88:89], v[88:89], v[170:171] op_sel_hi:[1,0]
	v_pk_mul_f32 v[86:87], v[86:87], v[170:171] op_sel_hi:[1,0]
	v_pk_mul_f32 v[84:85], v[84:85], v[170:171] op_sel_hi:[1,0]
	v_pk_mul_f32 v[82:83], v[82:83], v[170:171] op_sel_hi:[1,0]
	s_mov_b32 s3, s77
	s_waitcnt vmcnt(0)
	v_pk_mul_f32 v[138:139], s[8:9], v[162:163] op_sel_hi:[0,1]
	v_pk_mul_f32 v[140:141], s[8:9], v[158:159] op_sel_hi:[0,1]
	v_pk_mul_f32 v[158:159], s[8:9], v[164:165] op_sel_hi:[0,1]
	v_pk_mul_f32 v[160:161], s[8:9], v[160:161] op_sel_hi:[0,1]
	v_pk_mul_f32 v[162:163], s[8:9], v[220:221] op_sel_hi:[0,1]
	v_pk_mul_f32 v[168:169], s[8:9], v[226:227] op_sel_hi:[0,1]
	v_pk_mul_f32 v[166:167], s[8:9], v[222:223] op_sel_hi:[0,1]
	v_pk_mul_f32 v[174:175], v[114:115], v[198:199] op_sel_hi:[1,0]
	v_pk_mul_f32 v[114:115], v[120:121], v[198:199] op_sel_hi:[1,0]
	v_pk_mul_f32 v[176:177], v[118:119], v[198:199] op_sel_hi:[1,0]
	v_pk_mul_f32 v[118:119], v[124:125], v[198:199] op_sel_hi:[1,0]
	v_pk_mul_f32 v[120:121], v[128:129], v[198:199] op_sel_hi:[1,0]
	v_pk_mul_f32 v[124:125], v[126:127], v[198:199] op_sel_hi:[1,0]
	v_pk_mul_f32 v[126:127], v[114:115], v[114:115]
	v_pk_mul_f32 v[128:129], v[176:177], v[176:177]
	v_pk_mul_f32 v[198:199], v[120:121], v[120:121]
	v_pk_mul_f32 v[202:203], v[124:125], v[124:125]
	v_pk_fma_f32 v[126:127], v[116:117], v[116:117], v[126:127]
	v_pk_fma_f32 v[128:129], v[174:175], v[174:175], v[128:129]
	v_pk_fma_f32 v[198:199], v[118:119], v[118:119], v[198:199]
	v_pk_fma_f32 v[202:203], v[122:123], v[122:123], v[202:203]
	v_pk_add_f32 v[126:127], v[126:127], v[198:199]
	v_pk_add_f32 v[128:129], v[128:129], v[202:203]
	v_pk_mul_f32 v[202:203], v[110:111], v[110:111]
	v_pk_mov_b32 v[198:199], v[128:129], v[126:127] op_sel:[1,0]
	v_mov_b32_e32 v129, v127
	v_pk_add_f32 v[198:199], v[198:199], v[128:129]
	v_pk_mul_f32 v[128:129], v[102:103], v[200:201] op_sel_hi:[1,0]
	v_pk_mul_f32 v[102:103], v[108:109], v[200:201] op_sel_hi:[1,0]
	v_pk_mul_f32 v[108:109], v[106:107], v[200:201] op_sel_hi:[1,0]
	v_pk_mul_f32 v[106:107], v[112:113], v[200:201] op_sel_hi:[1,0]
	v_pk_mul_f32 v[126:127], v[98:99], v[200:201] op_sel_hi:[1,0]
	v_pk_mul_f32 v[98:99], v[104:105], v[104:105]
	v_pk_mul_f32 v[112:113], v[128:129], v[128:129]
	v_pk_mul_f32 v[200:201], v[106:107], v[106:107]
	v_pk_fma_f32 v[98:99], v[100:101], v[100:101], v[98:99]
	v_pk_fma_f32 v[112:113], v[126:127], v[126:127], v[112:113]
	v_pk_fma_f32 v[200:201], v[102:103], v[102:103], v[200:201]
	v_pk_fma_f32 v[202:203], v[108:109], v[108:109], v[202:203]
	v_pk_add_f32 v[98:99], v[98:99], v[200:201]
	v_pk_add_f32 v[112:113], v[112:113], v[202:203]
	v_pk_mul_f32 v[164:165], s[8:9], v[224:225] op_sel_hi:[0,1]
	v_pk_mov_b32 v[200:201], v[112:113], v[98:99] op_sel:[1,0]
	v_mov_b32_e32 v113, v99
	v_pk_add_f32 v[98:99], v[200:201], v[112:113]
	v_mov_b32_e32 v113, v198
	v_mov_b32_e32 v112, v98
	v_mov_b32_e32 v198, v99
	v_pk_add_f32 v[98:99], v[112:113], v[198:199]
	ds_bpermute_b32 v113, v195, v99
	ds_bpermute_b32 v112, v195, v98
	s_mov_b32 s8, 0x3c800000
	s_waitcnt lgkmcnt(0)
	v_pk_add_f32 v[98:99], v[98:99], v[112:113]
	ds_bpermute_b32 v113, v171, v99
	ds_bpermute_b32 v112, v171, v98
	s_waitcnt lgkmcnt(0)
; __device__ __forceinline__ unsigned pk_bf16(float lo, float hi) { f32x2 v = {lo, hi}; bf16x2_t b = __builtin_convertvector(v, bf16x2_t); return __builtin_bit_cast(unsigned, b); }
;     __device__ __forceinline__ void operator()(const f32x4 (&acc)[2][2][4][2], const Unit& u, int wr, int wc, int fr, int fq, float rp0, float rp1, const f32x4& raw0, const f32x4& raw1, float& rn0, float& rn1) const {
;     ...
;                     const int roff = ai * HALF + m * 16; const float r = rs[m];
;                     const f32x4 v00 = acc[ai][0][m][0] * r, v01 = acc[ai][0][m][1] * r, v10 = acc[ai][1][m][0] * r, v11 = acc[ai][1][m][1] * r;
;                     const f32x4 sq4 = (v00 * v00 + v01 * v01) + (v10 * v10 + v11 * v11);
;                     float ss = (sq4[0] + sq4[1]) + (sq4[2] + sq4[3]);
;                     ss += __shfl_xor(ss, 16); ss += __shfl_xor(ss, 32);
;                     const float rr = rsqrtf(ss * (1.f / 64.f) + EPS);
;                     const f32x4 o00 = v00 * rr * g[0][0], o01 = v01 * rr * g[0][1], o10 = v10 * rr * g[1][0], o11 = v11 * rr * g[1][1];
;                     u32x4 w0, w1;
;                     w0.x = pk_bf16(o00[0], o00[1]); w0.y = pk_bf16(o00[2], o00[3]); w0.z = pk_bf16(o01[0], o01[1]); w0.w = pk_bf16(o01[2], o01[3]);
;                     w1.x = pk_bf16(o10[0], o10[1]); w1.y = pk_bf16(o10[2], o10[3]); w1.z = pk_bf16(o11[0], o11[1]); w1.w = pk_bf16(o11[2], o11[3]);
;                     *(u32x4*)(base + (size_t)roff * ld) = w0; *(u32x4*)(base + (size_t)roff * ld + 32) = w1;
	v_pk_add_f32 v[112:113], v[98:99], v[112:113]
	v_mov_b64_e32 v[98:99], s[6:7]
	v_pk_fma_f32 v[198:199], v[112:113], s[8:9], v[98:99] op_sel_hi:[1,0,0]
	s_nop 0
	v_mul_f32_e32 v112, 0x4b800000, v199
	v_cmp_gt_f32_e64 s[6:7], s89, v199
	v_cmp_gt_f32_e32 vcc, s89, v198
	s_nop 0
	v_cndmask_b32_e64 v112, v199, v112, s[6:7]
	v_rsq_f32_e32 v112, v112
	s_nop 0
	v_mul_f32_e32 v113, 0x45800000, v112
	v_cndmask_b32_e64 v112, v112, v113, s[6:7]
	v_pk_mul_f32 v[174:175], v[174:175], v[112:113] op_sel_hi:[1,0]
	v_pk_mul_f32 v[116:117], v[116:117], v[112:113] op_sel_hi:[1,0]
	v_pk_mul_f32 v[176:177], v[176:177], v[112:113] op_sel_hi:[1,0]
	v_pk_mul_f32 v[114:115], v[114:115], v[112:113] op_sel_hi:[1,0]
	v_pk_mul_f32 v[116:117], v[160:161], v[116:117]
	v_pk_mul_f32 v[174:175], v[140:141], v[174:175]
	v_pk_mul_f32 v[200:201], v[158:159], v[114:115]
	v_pk_mul_f32 v[114:115], v[138:139], v[176:177]
	v_pk_mul_f32 v[122:123], v[122:123], v[112:113] op_sel_hi:[1,0]
	v_pk_mul_f32 v[118:119], v[118:119], v[112:113] op_sel_hi:[1,0]
	v_pk_mul_f32 v[124:125], v[124:125], v[112:113] op_sel_hi:[1,0]
	v_pk_mul_f32 v[112:113], v[120:121], v[112:113] op_sel_hi:[1,0]
	v_pk_mul_f32 v[118:119], v[168:169], v[118:119]
	v_pk_mul_f32 v[122:123], v[164:165], v[122:123]
	v_pk_mul_f32 v[120:121], v[166:167], v[112:113]
	v_pk_mul_f32 v[124:125], v[162:163], v[124:125]
	v_cvt_pk_bf16_f32 v112, v174, v175
	v_cvt_pk_bf16_f32 v113, v116, v117
	v_cvt_pk_bf16_f32 v114, v114, v115
	v_cvt_pk_bf16_f32 v115, v200, v201
	v_cvt_pk_bf16_f32 v116, v122, v123
	v_cvt_pk_bf16_f32 v117, v118, v119
	v_cvt_pk_bf16_f32 v118, v124, v125
	v_cvt_pk_bf16_f32 v119, v120, v121
	global_store_dwordx4 v[156:157], v[112:115], off
	global_store_dwordx4 v[156:157], v[116:119], off offset:64
	s_nop 0
	v_mul_f32_e32 v112, 0x4b800000, v198
	v_cndmask_b32_e32 v112, v198, v112, vcc
	v_rsq_f32_e32 v112, v112
	s_nop 0
	v_mul_f32_e32 v113, 0x45800000, v112
	v_cndmask_b32_e32 v112, v112, v113, vcc
	v_pk_mul_f32 v[114:115], v[126:127], v[112:113] op_sel_hi:[1,0]
	v_pk_mul_f32 v[100:101], v[100:101], v[112:113] op_sel_hi:[1,0]
	v_pk_mul_f32 v[102:103], v[102:103], v[112:113] op_sel_hi:[1,0]
	v_pk_mul_f32 v[116:117], v[160:161], v[100:101]
	v_pk_mul_f32 v[100:101], v[140:141], v[114:115]
	v_pk_mul_f32 v[114:115], v[128:129], v[112:113] op_sel_hi:[1,0]
	v_pk_mul_f32 v[104:105], v[104:105], v[112:113] op_sel_hi:[1,0]
	v_pk_mul_f32 v[108:109], v[108:109], v[112:113] op_sel_hi:[1,0]
	v_pk_mul_f32 v[118:119], v[168:169], v[102:103]
	v_pk_mul_f32 v[102:103], v[110:111], v[112:113] op_sel_hi:[1,0]
	v_pk_mul_f32 v[106:107], v[106:107], v[112:113] op_sel_hi:[1,0]
	v_pk_mul_f32 v[104:105], v[158:159], v[104:105]
	v_pk_mul_f32 v[114:115], v[138:139], v[114:115]
	v_pk_mul_f32 v[108:109], v[164:165], v[108:109]
	v_pk_mul_f32 v[110:111], v[166:167], v[106:107]
	v_pk_mul_f32 v[106:107], v[162:163], v[102:103]
	v_cvt_pk_bf16_f32 v100, v100, v101
	v_cvt_pk_bf16_f32 v101, v116, v117
	v_cvt_pk_bf16_f32 v102, v114, v115
	v_cvt_pk_bf16_f32 v103, v104, v105
	v_cvt_pk_bf16_f32 v104, v108, v109
	v_cvt_pk_bf16_f32 v105, v118, v119
	v_cvt_pk_bf16_f32 v106, v106, v107
	v_cvt_pk_bf16_f32 v107, v110, v111
	v_lshl_add_u64 v[108:109], v[156:157], 0, s[76:77]
	global_store_dwordx4 v[108:109], v[100:103], off
	global_store_dwordx4 v[108:109], v[104:107], off offset:64
	v_pk_mul_f32 v[110:111], v[70:71], v[170:171] op_sel_hi:[1,0]
	v_pk_mul_f32 v[100:101], v[80:81], v[80:81]
	v_pk_mul_f32 v[102:103], v[78:79], v[78:79]
	v_pk_mul_f32 v[104:105], v[96:97], v[96:97]
	v_pk_mul_f32 v[106:107], v[94:95], v[94:95]
	v_pk_fma_f32 v[100:101], v[76:77], v[76:77], v[100:101]
	v_pk_fma_f32 v[102:103], v[74:75], v[74:75], v[102:103]
	v_pk_fma_f32 v[104:105], v[92:93], v[92:93], v[104:105]
	v_pk_fma_f32 v[106:107], v[90:91], v[90:91], v[106:107]
	v_pk_add_f32 v[100:101], v[100:101], v[104:105]
	v_pk_add_f32 v[102:103], v[102:103], v[106:107]
	v_pk_mul_f32 v[106:107], v[66:67], v[170:171] op_sel_hi:[1,0]
	v_pk_mov_b32 v[104:105], v[102:103], v[100:101] op_sel:[1,0]
	v_mov_b32_e32 v103, v101
	v_pk_add_f32 v[100:101], v[104:105], v[102:103]
	v_lshl_add_u64 v[102:103], v[108:109], 0, s[76:77]
	v_pk_mul_f32 v[108:109], v[72:73], v[170:171] op_sel_hi:[1,0]
	v_pk_mul_f32 v[104:105], v[68:69], v[170:171] op_sel_hi:[1,0]
	v_pk_mul_f32 v[66:67], v[108:109], v[108:109]
	v_pk_mul_f32 v[68:69], v[110:111], v[110:111]
	v_pk_mul_f32 v[70:71], v[88:89], v[88:89]
	v_pk_mul_f32 v[72:73], v[86:87], v[86:87]
	v_pk_fma_f32 v[66:67], v[104:105], v[104:105], v[66:67]
	v_pk_fma_f32 v[68:69], v[106:107], v[106:107], v[68:69]
	v_pk_fma_f32 v[70:71], v[84:85], v[84:85], v[70:71]
	v_pk_fma_f32 v[72:73], v[82:83], v[82:83], v[72:73]
	v_pk_add_f32 v[66:67], v[66:67], v[70:71]
	v_pk_add_f32 v[68:69], v[68:69], v[72:73]
	s_nop 0
	v_pk_mov_b32 v[70:71], v[68:69], v[66:67] op_sel:[1,0]
	v_mov_b32_e32 v69, v67
	v_pk_add_f32 v[66:67], v[70:71], v[68:69]
	v_mov_b32_e32 v69, v100
	v_mov_b32_e32 v68, v66
	v_mov_b32_e32 v100, v67
	v_pk_add_f32 v[66:67], v[68:69], v[100:101]
	ds_bpermute_b32 v69, v195, v67
	ds_bpermute_b32 v68, v195, v66
	s_waitcnt lgkmcnt(0)
	v_pk_add_f32 v[66:67], v[66:67], v[68:69]
	ds_bpermute_b32 v69, v171, v67
	ds_bpermute_b32 v68, v171, v66
	s_waitcnt lgkmcnt(0)
; __device__ __forceinline__ unsigned pk_bf16(float lo, float hi) { f32x2 v = {lo, hi}; bf16x2_t b = __builtin_convertvector(v, bf16x2_t); return __builtin_bit_cast(unsigned, b); }
;     __device__ __forceinline__ void operator()(const f32x4 (&acc)[2][2][4][2], const Unit& u, int wr, int wc, int fr, int fq, float rp0, float rp1, const f32x4& raw0, const f32x4& raw1, float& rn0, float& rn1) const {
;     ...
;                     const int roff = ai * HALF + m * 16; const float r = rs[m];
;                     const f32x4 v00 = acc[ai][0][m][0] * r, v01 = acc[ai][0][m][1] * r, v10 = acc[ai][1][m][0] * r, v11 = acc[ai][1][m][1] * r;
;                     const f32x4 sq4 = (v00 * v00 + v01 * v01) + (v10 * v10 + v11 * v11);
;                     float ss = (sq4[0] + sq4[1]) + (sq4[2] + sq4[3]);
;                     ss += __shfl_xor(ss, 16); ss += __shfl_xor(ss, 32);
;                     const float rr = rsqrtf(ss * (1.f / 64.f) + EPS);
;                     const f32x4 o00 = v00 * rr * g[0][0], o01 = v01 * rr * g[0][1], o10 = v10 * rr * g[1][0], o11 = v11 * rr * g[1][1];
;                     u32x4 w0, w1;
;                     w0.x = pk_bf16(o00[0], o00[1]); w0.y = pk_bf16(o00[2], o00[3]); w0.z = pk_bf16(o01[0], o01[1]); w0.w = pk_bf16(o01[2], o01[3]);
;                     w1.x = pk_bf16(o10[0], o10[1]); w1.y = pk_bf16(o10[2], o10[3]); w1.z = pk_bf16(o11[0], o11[1]); w1.w = pk_bf16(o11[2], o11[3]);
;                     *(u32x4*)(base + (size_t)roff * ld) = w0; *(u32x4*)(base + (size_t)roff * ld + 32) = w1;
	v_pk_add_f32 v[66:67], v[66:67], v[68:69]
	s_nop 0
	v_pk_fma_f32 v[100:101], v[66:67], s[8:9], v[98:99] op_sel_hi:[1,0,0]
	s_nop 0
	v_mul_f32_e32 v66, 0x4b800000, v101
	v_cmp_gt_f32_e64 s[6:7], s89, v101
	v_cmp_gt_f32_e32 vcc, s89, v100
	s_nop 0
	v_cndmask_b32_e64 v66, v101, v66, s[6:7]
	v_rsq_f32_e32 v66, v66
	s_nop 0
	v_mul_f32_e32 v67, 0x45800000, v66
	v_cndmask_b32_e64 v66, v66, v67, s[6:7]
	v_pk_mul_f32 v[68:69], v[74:75], v[66:67] op_sel_hi:[1,0]
	v_pk_mul_f32 v[70:71], v[76:77], v[66:67] op_sel_hi:[1,0]
	v_pk_mul_f32 v[72:73], v[78:79], v[66:67] op_sel_hi:[1,0]
	v_pk_mul_f32 v[74:75], v[80:81], v[66:67] op_sel_hi:[1,0]
	v_pk_mul_f32 v[70:71], v[160:161], v[70:71]
	v_pk_mul_f32 v[68:69], v[140:141], v[68:69]
	v_pk_mul_f32 v[74:75], v[158:159], v[74:75]
	v_pk_mul_f32 v[72:73], v[138:139], v[72:73]
	v_pk_mul_f32 v[76:77], v[90:91], v[66:67] op_sel_hi:[1,0]
	v_pk_mul_f32 v[78:79], v[92:93], v[66:67] op_sel_hi:[1,0]
	v_pk_mul_f32 v[80:81], v[94:95], v[66:67] op_sel_hi:[1,0]
	v_pk_mul_f32 v[66:67], v[96:97], v[66:67] op_sel_hi:[1,0]
	v_pk_mul_f32 v[78:79], v[168:169], v[78:79]
	v_pk_mul_f32 v[76:77], v[164:165], v[76:77]
	v_pk_mul_f32 v[90:91], v[166:167], v[66:67]
	v_pk_mul_f32 v[80:81], v[162:163], v[80:81]
	v_cvt_pk_bf16_f32 v66, v68, v69
	v_cvt_pk_bf16_f32 v67, v70, v71
	v_cvt_pk_bf16_f32 v68, v72, v73
	v_cvt_pk_bf16_f32 v69, v74, v75
	v_cvt_pk_bf16_f32 v70, v76, v77
	v_cvt_pk_bf16_f32 v71, v78, v79
	v_cvt_pk_bf16_f32 v72, v80, v81
	v_cvt_pk_bf16_f32 v73, v90, v91
	global_store_dwordx4 v[102:103], v[66:69], off
	global_store_dwordx4 v[102:103], v[70:73], off offset:64
	s_nop 0
	v_mul_f32_e32 v66, 0x4b800000, v100
	v_cndmask_b32_e32 v66, v100, v66, vcc
	v_rsq_f32_e32 v66, v66
	s_nop 0
	v_mul_f32_e32 v67, 0x45800000, v66
	v_cndmask_b32_e32 v66, v66, v67, vcc
	v_pk_mul_f32 v[68:69], v[106:107], v[66:67] op_sel_hi:[1,0]
	v_pk_mul_f32 v[70:71], v[104:105], v[66:67] op_sel_hi:[1,0]
	v_pk_mul_f32 v[72:73], v[110:111], v[66:67] op_sel_hi:[1,0]
	v_pk_mul_f32 v[74:75], v[108:109], v[66:67] op_sel_hi:[1,0]
	v_pk_mul_f32 v[76:77], v[82:83], v[66:67] op_sel_hi:[1,0]
	v_pk_mul_f32 v[70:71], v[160:161], v[70:71]
	v_pk_mul_f32 v[68:69], v[140:141], v[68:69]
	v_pk_mul_f32 v[74:75], v[158:159], v[74:75]
	v_pk_mul_f32 v[72:73], v[138:139], v[72:73]
	v_pk_mul_f32 v[78:79], v[84:85], v[66:67] op_sel_hi:[1,0]
	v_pk_mul_f32 v[76:77], v[164:165], v[76:77]
	v_pk_mul_f32 v[80:81], v[86:87], v[66:67] op_sel_hi:[1,0]
	v_pk_mul_f32 v[66:67], v[88:89], v[66:67] op_sel_hi:[1,0]
	v_pk_mul_f32 v[78:79], v[168:169], v[78:79]
	v_pk_mul_f32 v[82:83], v[166:167], v[66:67]
	v_pk_mul_f32 v[80:81], v[162:163], v[80:81]
	v_cvt_pk_bf16_f32 v66, v68, v69
	v_cvt_pk_bf16_f32 v67, v70, v71
	v_cvt_pk_bf16_f32 v68, v72, v73
	v_cvt_pk_bf16_f32 v69, v74, v75
	v_cvt_pk_bf16_f32 v70, v76, v77
	v_lshl_add_u64 v[74:75], v[102:103], 0, s[76:77]
	v_cvt_pk_bf16_f32 v71, v78, v79
	v_cvt_pk_bf16_f32 v72, v80, v81
	v_cvt_pk_bf16_f32 v73, v82, v83
	global_store_dwordx4 v[74:75], v[66:69], off
	global_store_dwordx4 v[74:75], v[70:73], off offset:64
	ds_bpermute_b32 v70, v196, v154
	ds_bpermute_b32 v72, v196, v154 offset:64
	v_mad_u64_u32 v[74:75], s[6:7], s10, v217, v[74:75]
	ds_bpermute_b32 v68, v196, v154 offset:128
	s_waitcnt lgkmcnt(2)
	v_pk_mul_f32 v[48:49], v[48:49], v[70:71] op_sel_hi:[1,0]
	v_pk_mul_f32 v[46:47], v[46:47], v[70:71] op_sel_hi:[1,0]
	v_pk_mul_f32 v[64:65], v[64:65], v[70:71] op_sel_hi:[1,0]
	v_pk_mul_f32 v[62:63], v[62:63], v[70:71] op_sel_hi:[1,0]
	v_pk_mul_f32 v[44:45], v[44:45], v[70:71] op_sel_hi:[1,0]
	v_pk_mul_f32 v[42:43], v[42:43], v[70:71] op_sel_hi:[1,0]
	v_pk_mul_f32 v[60:61], v[60:61], v[70:71] op_sel_hi:[1,0]
	v_pk_mul_f32 v[58:59], v[58:59], v[70:71] op_sel_hi:[1,0]
	v_pk_mul_f32 v[70:71], v[48:49], v[48:49]
	v_pk_mul_f32 v[76:77], v[46:47], v[46:47]
	v_pk_mul_f32 v[78:79], v[64:65], v[64:65]
	v_pk_mul_f32 v[80:81], v[62:63], v[62:63]
	v_pk_fma_f32 v[70:71], v[44:45], v[44:45], v[70:71]
	v_pk_fma_f32 v[76:77], v[42:43], v[42:43], v[76:77]
	v_pk_fma_f32 v[78:79], v[60:61], v[60:61], v[78:79]
	v_pk_fma_f32 v[80:81], v[58:59], v[58:59], v[80:81]
	v_pk_add_f32 v[70:71], v[70:71], v[78:79]
	v_pk_add_f32 v[76:77], v[76:77], v[80:81]
	s_waitcnt lgkmcnt(1)
	v_pk_mul_f32 v[80:81], v[40:41], v[72:73] op_sel_hi:[1,0]
	v_pk_mov_b32 v[78:79], v[76:77], v[70:71] op_sel:[1,0]
	v_mov_b32_e32 v77, v71
	v_pk_mul_f32 v[82:83], v[38:39], v[72:73] op_sel_hi:[1,0]
	v_pk_mul_f32 v[56:57], v[56:57], v[72:73] op_sel_hi:[1,0]
	v_pk_mul_f32 v[54:55], v[54:55], v[72:73] op_sel_hi:[1,0]
	v_pk_add_f32 v[70:71], v[78:79], v[76:77]
	v_pk_mul_f32 v[76:77], v[36:37], v[72:73] op_sel_hi:[1,0]
	v_pk_mul_f32 v[78:79], v[34:35], v[72:73] op_sel_hi:[1,0]
	v_pk_mul_f32 v[52:53], v[52:53], v[72:73] op_sel_hi:[1,0]
	v_pk_mul_f32 v[50:51], v[50:51], v[72:73] op_sel_hi:[1,0]
	v_pk_mul_f32 v[34:35], v[80:81], v[80:81]
	v_pk_mul_f32 v[36:37], v[82:83], v[82:83]
	v_pk_mul_f32 v[38:39], v[56:57], v[56:57]
	v_pk_mul_f32 v[40:41], v[54:55], v[54:55]
	v_pk_fma_f32 v[34:35], v[76:77], v[76:77], v[34:35]
	v_pk_fma_f32 v[36:37], v[78:79], v[78:79], v[36:37]
	v_pk_fma_f32 v[38:39], v[52:53], v[52:53], v[38:39]
	v_pk_fma_f32 v[40:41], v[50:51], v[50:51], v[40:41]
	v_pk_add_f32 v[34:35], v[34:35], v[38:39]
	v_pk_add_f32 v[36:37], v[36:37], v[40:41]
	ds_bpermute_b32 v66, v196, v154 offset:192
	v_pk_mov_b32 v[38:39], v[36:37], v[34:35] op_sel:[1,0]
	v_mov_b32_e32 v37, v35
	v_pk_add_f32 v[34:35], v[38:39], v[36:37]
	v_mov_b32_e32 v37, v70
	v_mov_b32_e32 v36, v34
	v_mov_b32_e32 v70, v35
	v_pk_add_f32 v[34:35], v[36:37], v[70:71]
	ds_bpermute_b32 v37, v195, v35
	ds_bpermute_b32 v36, v195, v34
	s_waitcnt lgkmcnt(3)
; __device__ __forceinline__ unsigned pk_bf16(float lo, float hi) { f32x2 v = {lo, hi}; bf16x2_t b = __builtin_convertvector(v, bf16x2_t); return __builtin_bit_cast(unsigned, b); }
;     __device__ __forceinline__ void operator()(const f32x4 (&acc)[2][2][4][2], const Unit& u, int wr, int wc, int fr, int fq, float rp0, float rp1, const f32x4& raw0, const f32x4& raw1, float& rn0, float& rn1) const {
;     ...
;                 for (int m = 0; m < 4; ++m) {
;                     const int roff = ai * HALF + m * 16; const float r = rs[m];
;                     const f32x4 v00 = acc[ai][0][m][0] * r, v01 = acc[ai][0][m][1] * r, v10 = acc[ai][1][m][0] * r, v11 = acc[ai][1][m][1] * r;
;                     const f32x4 sq4 = (v00 * v00 + v01 * v01) + (v10 * v10 + v11 * v11);
;                     float ss = (sq4[0] + sq4[1]) + (sq4[2] + sq4[3]);
;                     ss += __shfl_xor(ss, 16); ss += __shfl_xor(ss, 32);
;                     const float rr = rsqrtf(ss * (1.f / 64.f) + EPS);
;                     const f32x4 o00 = v00 * rr * g[0][0], o01 = v01 * rr * g[0][1], o10 = v10 * rr * g[1][0], o11 = v11 * rr * g[1][1];
;                     u32x4 w0, w1;
;                     w0.x = pk_bf16(o00[0], o00[1]); w0.y = pk_bf16(o00[2], o00[3]); w0.z = pk_bf16(o01[0], o01[1]); w0.w = pk_bf16(o01[2], o01[3]);
;                     w1.x = pk_bf16(o10[0], o10[1]); w1.y = pk_bf16(o10[2], o10[3]); w1.z = pk_bf16(o11[0], o11[1]); w1.w = pk_bf16(o11[2], o11[3]);
;                     *(u32x4*)(base + (size_t)roff * ld) = w0; *(u32x4*)(base + (size_t)roff * ld + 32) = w1;
	v_pk_mul_f32 v[16:17], v[16:17], v[68:69] op_sel_hi:[1,0]
	v_pk_mul_f32 v[14:15], v[14:15], v[68:69] op_sel_hi:[1,0]
	v_pk_mul_f32 v[32:33], v[32:33], v[68:69] op_sel_hi:[1,0]
	v_pk_mul_f32 v[30:31], v[30:31], v[68:69] op_sel_hi:[1,0]
	s_waitcnt lgkmcnt(0)
	v_pk_add_f32 v[34:35], v[34:35], v[36:37]
	ds_bpermute_b32 v37, v171, v35
	ds_bpermute_b32 v36, v171, v34
	v_pk_mul_f32 v[12:13], v[12:13], v[68:69] op_sel_hi:[1,0]
	v_pk_mul_f32 v[10:11], v[10:11], v[68:69] op_sel_hi:[1,0]
	v_pk_mul_f32 v[28:29], v[28:29], v[68:69] op_sel_hi:[1,0]
	v_pk_mul_f32 v[26:27], v[26:27], v[68:69] op_sel_hi:[1,0]
	s_waitcnt lgkmcnt(0)
	v_pk_add_f32 v[34:35], v[34:35], v[36:37]
	v_pk_mul_f32 v[24:25], v[24:25], v[66:67] op_sel_hi:[1,0]
	v_pk_fma_f32 v[70:71], v[34:35], s[8:9], v[98:99] op_sel_hi:[1,0,0]
	v_pk_mul_f32 v[22:23], v[22:23], v[66:67] op_sel_hi:[1,0]
	v_mul_f32_e32 v34, 0x4b800000, v71
	v_cmp_gt_f32_e64 s[6:7], s89, v71
	v_cmp_gt_f32_e32 vcc, s89, v70
	v_pk_mul_f32 v[20:21], v[20:21], v[66:67] op_sel_hi:[1,0]
	v_cndmask_b32_e64 v34, v71, v34, s[6:7]
	v_rsq_f32_e32 v34, v34
	v_pk_mul_f32 v[18:19], v[18:19], v[66:67] op_sel_hi:[1,0]
	v_mul_f32_e32 v35, 0x45800000, v34
	v_cndmask_b32_e64 v34, v34, v35, s[6:7]
	v_pk_mul_f32 v[36:37], v[42:43], v[34:35] op_sel_hi:[1,0]
	v_pk_mul_f32 v[38:39], v[44:45], v[34:35] op_sel_hi:[1,0]
	v_pk_mul_f32 v[40:41], v[46:47], v[34:35] op_sel_hi:[1,0]
	v_pk_mul_f32 v[42:43], v[48:49], v[34:35] op_sel_hi:[1,0]
	v_pk_mul_f32 v[38:39], v[160:161], v[38:39]
	v_pk_mul_f32 v[36:37], v[140:141], v[36:37]
	v_pk_mul_f32 v[42:43], v[158:159], v[42:43]
	v_pk_mul_f32 v[40:41], v[138:139], v[40:41]
	v_pk_mul_f32 v[44:45], v[58:59], v[34:35] op_sel_hi:[1,0]
	v_pk_mul_f32 v[46:47], v[60:61], v[34:35] op_sel_hi:[1,0]
	v_pk_mul_f32 v[48:49], v[62:63], v[34:35] op_sel_hi:[1,0]
	v_pk_mul_f32 v[34:35], v[64:65], v[34:35] op_sel_hi:[1,0]
	v_pk_mul_f32 v[46:47], v[168:169], v[46:47]
	v_pk_mul_f32 v[44:45], v[164:165], v[44:45]
	v_pk_mul_f32 v[58:59], v[166:167], v[34:35]
	v_pk_mul_f32 v[48:49], v[162:163], v[48:49]
	v_cvt_pk_bf16_f32 v34, v36, v37
	v_cvt_pk_bf16_f32 v35, v38, v39
	v_cvt_pk_bf16_f32 v36, v40, v41
	v_cvt_pk_bf16_f32 v37, v42, v43
	v_cvt_pk_bf16_f32 v38, v44, v45
	v_cvt_pk_bf16_f32 v39, v46, v47
	v_cvt_pk_bf16_f32 v40, v48, v49
	v_cvt_pk_bf16_f32 v41, v58, v59
	global_store_dwordx4 v[74:75], v[34:37], off
	global_store_dwordx4 v[74:75], v[38:41], off offset:64
	s_nop 0
	v_mul_f32_e32 v34, 0x4b800000, v70
	v_cndmask_b32_e32 v34, v70, v34, vcc
	v_rsq_f32_e32 v34, v34
	s_nop 0
	v_mul_f32_e32 v35, 0x45800000, v34
	v_cndmask_b32_e32 v34, v34, v35, vcc
	v_pk_mul_f32 v[36:37], v[78:79], v[34:35] op_sel_hi:[1,0]
	v_pk_mul_f32 v[38:39], v[76:77], v[34:35] op_sel_hi:[1,0]
	v_pk_mul_f32 v[40:41], v[82:83], v[34:35] op_sel_hi:[1,0]
	v_pk_mul_f32 v[42:43], v[80:81], v[34:35] op_sel_hi:[1,0]
	v_pk_mul_f32 v[44:45], v[50:51], v[34:35] op_sel_hi:[1,0]
	v_pk_mul_f32 v[46:47], v[52:53], v[34:35] op_sel_hi:[1,0]
	v_pk_mul_f32 v[48:49], v[54:55], v[34:35] op_sel_hi:[1,0]
	v_pk_mul_f32 v[34:35], v[56:57], v[34:35] op_sel_hi:[1,0]
	v_pk_mul_f32 v[38:39], v[160:161], v[38:39]
	v_pk_mul_f32 v[36:37], v[140:141], v[36:37]
	v_pk_mul_f32 v[42:43], v[158:159], v[42:43]
	v_pk_mul_f32 v[40:41], v[138:139], v[40:41]
	v_pk_mul_f32 v[46:47], v[168:169], v[46:47]
	v_pk_mul_f32 v[44:45], v[164:165], v[44:45]
	v_pk_mul_f32 v[50:51], v[166:167], v[34:35]
	v_pk_mul_f32 v[48:49], v[162:163], v[48:49]
	v_cvt_pk_bf16_f32 v34, v36, v37
	v_cvt_pk_bf16_f32 v35, v38, v39
	v_cvt_pk_bf16_f32 v36, v40, v41
	v_cvt_pk_bf16_f32 v37, v42, v43
	v_cvt_pk_bf16_f32 v38, v44, v45
	v_cvt_pk_bf16_f32 v39, v46, v47
	v_cvt_pk_bf16_f32 v40, v48, v49
	v_cvt_pk_bf16_f32 v41, v50, v51
	v_lshl_add_u64 v[42:43], v[74:75], 0, s[76:77]
	global_store_dwordx4 v[42:43], v[34:37], off
	global_store_dwordx4 v[42:43], v[38:41], off offset:64
	v_pk_mul_f32 v[44:45], v[6:7], v[66:67] op_sel_hi:[1,0]
	v_pk_mul_f32 v[34:35], v[16:17], v[16:17]
	v_pk_mul_f32 v[36:37], v[14:15], v[14:15]
	v_pk_mul_f32 v[38:39], v[32:33], v[32:33]
	v_pk_mul_f32 v[40:41], v[30:31], v[30:31]
	v_pk_fma_f32 v[34:35], v[12:13], v[12:13], v[34:35]
	v_pk_fma_f32 v[36:37], v[10:11], v[10:11], v[36:37]
	v_pk_fma_f32 v[38:39], v[28:29], v[28:29], v[38:39]
	v_pk_fma_f32 v[40:41], v[26:27], v[26:27], v[40:41]
	v_pk_add_f32 v[34:35], v[34:35], v[38:39]
	v_pk_add_f32 v[36:37], v[36:37], v[40:41]
	v_pk_mul_f32 v[40:41], v[2:3], v[66:67] op_sel_hi:[1,0]
	v_pk_mov_b32 v[38:39], v[36:37], v[34:35] op_sel:[1,0]
	v_mov_b32_e32 v37, v35
	v_pk_add_f32 v[34:35], v[38:39], v[36:37]
	v_lshl_add_u64 v[36:37], v[42:43], 0, s[76:77]
	v_pk_mul_f32 v[42:43], v[8:9], v[66:67] op_sel_hi:[1,0]
	v_pk_mul_f32 v[38:39], v[4:5], v[66:67] op_sel_hi:[1,0]
	v_pk_mul_f32 v[2:3], v[42:43], v[42:43]
	v_pk_mul_f32 v[4:5], v[44:45], v[44:45]
	v_pk_mul_f32 v[6:7], v[24:25], v[24:25]
	v_pk_mul_f32 v[8:9], v[22:23], v[22:23]
	v_pk_fma_f32 v[2:3], v[38:39], v[38:39], v[2:3]
	v_pk_fma_f32 v[4:5], v[40:41], v[40:41], v[4:5]
	v_pk_fma_f32 v[6:7], v[20:21], v[20:21], v[6:7]
	v_pk_fma_f32 v[8:9], v[18:19], v[18:19], v[8:9]
	v_pk_add_f32 v[2:3], v[2:3], v[6:7]
	v_pk_add_f32 v[4:5], v[4:5], v[8:9]
	s_nop 0
	v_pk_mov_b32 v[6:7], v[4:5], v[2:3] op_sel:[1,0]
	v_mov_b32_e32 v5, v3
	v_pk_add_f32 v[2:3], v[6:7], v[4:5]
	v_mov_b32_e32 v5, v34
	v_mov_b32_e32 v4, v2
	v_mov_b32_e32 v34, v3
	v_pk_add_f32 v[2:3], v[4:5], v[34:35]
	ds_bpermute_b32 v5, v195, v3
	ds_bpermute_b32 v4, v195, v2
	s_waitcnt lgkmcnt(0)
; __device__ __forceinline__ unsigned pk_bf16(float lo, float hi) { f32x2 v = {lo, hi}; bf16x2_t b = __builtin_convertvector(v, bf16x2_t); return __builtin_bit_cast(unsigned, b); }
;     __device__ __forceinline__ void operator()(const f32x4 (&acc)[2][2][4][2], const Unit& u, int wr, int wc, int fr, int fq, float rp0, float rp1, const f32x4& raw0, const f32x4& raw1, float& rn0, float& rn1) const {
;     ...
;                 for (int m = 0; m < 4; ++m) {
;                     const int roff = ai * HALF + m * 16; const float r = rs[m];
;                     const f32x4 v00 = acc[ai][0][m][0] * r, v01 = acc[ai][0][m][1] * r, v10 = acc[ai][1][m][0] * r, v11 = acc[ai][1][m][1] * r;
;                     const f32x4 sq4 = (v00 * v00 + v01 * v01) + (v10 * v10 + v11 * v11);
;                     float ss = (sq4[0] + sq4[1]) + (sq4[2] + sq4[3]);
;                     ss += __shfl_xor(ss, 16); ss += __shfl_xor(ss, 32);
;                     const float rr = rsqrtf(ss * (1.f / 64.f) + EPS);
;                     const f32x4 o00 = v00 * rr * g[0][0], o01 = v01 * rr * g[0][1], o10 = v10 * rr * g[1][0], o11 = v11 * rr * g[1][1];
;                     u32x4 w0, w1;
;                     w0.x = pk_bf16(o00[0], o00[1]); w0.y = pk_bf16(o00[2], o00[3]); w0.z = pk_bf16(o01[0], o01[1]); w0.w = pk_bf16(o01[2], o01[3]);
;                     w1.x = pk_bf16(o10[0], o10[1]); w1.y = pk_bf16(o10[2], o10[3]); w1.z = pk_bf16(o11[0], o11[1]); w1.w = pk_bf16(o11[2], o11[3]);
;                     *(u32x4*)(base + (size_t)roff * ld) = w0; *(u32x4*)(base + (size_t)roff * ld + 32) = w1;
	v_pk_add_f32 v[2:3], v[2:3], v[4:5]
	ds_bpermute_b32 v5, v171, v3
	ds_bpermute_b32 v4, v171, v2
	s_waitcnt lgkmcnt(0)
	v_pk_add_f32 v[2:3], v[2:3], v[4:5]
	s_nop 0
	v_pk_fma_f32 v[34:35], v[2:3], s[8:9], v[98:99] op_sel_hi:[1,0,0]
	s_nop 0
	v_mul_f32_e32 v2, 0x4b800000, v35
	v_cmp_gt_f32_e64 s[6:7], s89, v35
	v_cmp_gt_f32_e32 vcc, s89, v34
	s_nop 0
	v_cndmask_b32_e64 v2, v35, v2, s[6:7]
	v_rsq_f32_e32 v2, v2
	s_nop 0
	v_mul_f32_e32 v3, 0x45800000, v2
	v_cndmask_b32_e64 v2, v2, v3, s[6:7]
	v_pk_mul_f32 v[4:5], v[10:11], v[2:3] op_sel_hi:[1,0]
	v_pk_mul_f32 v[6:7], v[12:13], v[2:3] op_sel_hi:[1,0]
	v_pk_mul_f32 v[8:9], v[14:15], v[2:3] op_sel_hi:[1,0]
	v_pk_mul_f32 v[10:11], v[16:17], v[2:3] op_sel_hi:[1,0]
	v_pk_mul_f32 v[6:7], v[160:161], v[6:7]
	v_pk_mul_f32 v[4:5], v[140:141], v[4:5]
	v_pk_mul_f32 v[10:11], v[158:159], v[10:11]
	v_pk_mul_f32 v[8:9], v[138:139], v[8:9]
	v_pk_mul_f32 v[12:13], v[26:27], v[2:3] op_sel_hi:[1,0]
	v_pk_mul_f32 v[14:15], v[28:29], v[2:3] op_sel_hi:[1,0]
	v_pk_mul_f32 v[16:17], v[30:31], v[2:3] op_sel_hi:[1,0]
	v_pk_mul_f32 v[2:3], v[32:33], v[2:3] op_sel_hi:[1,0]
	v_pk_mul_f32 v[14:15], v[168:169], v[14:15]
	v_pk_mul_f32 v[12:13], v[164:165], v[12:13]
	v_pk_mul_f32 v[26:27], v[166:167], v[2:3]
	v_pk_mul_f32 v[16:17], v[162:163], v[16:17]
	v_cvt_pk_bf16_f32 v2, v4, v5
	v_cvt_pk_bf16_f32 v3, v6, v7
	v_cvt_pk_bf16_f32 v4, v8, v9
	v_cvt_pk_bf16_f32 v5, v10, v11
	v_cvt_pk_bf16_f32 v6, v12, v13
	v_cvt_pk_bf16_f32 v7, v14, v15
	v_cvt_pk_bf16_f32 v8, v16, v17
	v_cvt_pk_bf16_f32 v9, v26, v27
	global_store_dwordx4 v[36:37], v[2:5], off
	global_store_dwordx4 v[36:37], v[6:9], off offset:64
	s_nop 0
	v_mul_f32_e32 v2, 0x4b800000, v34
	v_cndmask_b32_e32 v2, v34, v2, vcc
	v_rsq_f32_e32 v2, v2
	s_nop 0
	v_mul_f32_e32 v3, 0x45800000, v2
	v_cndmask_b32_e32 v2, v2, v3, vcc
	v_pk_mul_f32 v[4:5], v[40:41], v[2:3] op_sel_hi:[1,0]
	v_pk_mul_f32 v[6:7], v[38:39], v[2:3] op_sel_hi:[1,0]
	v_pk_mul_f32 v[8:9], v[44:45], v[2:3] op_sel_hi:[1,0]
	v_pk_mul_f32 v[10:11], v[42:43], v[2:3] op_sel_hi:[1,0]
	v_pk_mul_f32 v[12:13], v[18:19], v[2:3] op_sel_hi:[1,0]
	v_pk_mul_f32 v[14:15], v[20:21], v[2:3] op_sel_hi:[1,0]
	v_pk_mul_f32 v[16:17], v[22:23], v[2:3] op_sel_hi:[1,0]
	v_pk_mul_f32 v[2:3], v[24:25], v[2:3] op_sel_hi:[1,0]
	v_pk_mul_f32 v[6:7], v[160:161], v[6:7]
	v_pk_mul_f32 v[4:5], v[140:141], v[4:5]
	v_pk_mul_f32 v[10:11], v[158:159], v[10:11]
	v_pk_mul_f32 v[8:9], v[138:139], v[8:9]
	v_pk_mul_f32 v[14:15], v[168:169], v[14:15]
	v_pk_mul_f32 v[12:13], v[164:165], v[12:13]
	v_pk_mul_f32 v[18:19], v[166:167], v[2:3]
	v_pk_mul_f32 v[16:17], v[162:163], v[16:17]
	v_cvt_pk_bf16_f32 v2, v4, v5
	v_cvt_pk_bf16_f32 v3, v6, v7
	v_cvt_pk_bf16_f32 v4, v8, v9
	v_cvt_pk_bf16_f32 v5, v10, v11
	v_cvt_pk_bf16_f32 v138, v12, v13
	v_cvt_pk_bf16_f32 v139, v14, v15
	v_cvt_pk_bf16_f32 v140, v16, v17
	v_cvt_pk_bf16_f32 v141, v18, v19
	v_lshl_add_u64 v[6:7], v[36:37], 0, s[76:77]
	global_store_dwordx4 v[6:7], v[2:5], off
